# attention inner loop (pong copy) QK section: K/Q fragment LDS reads prefetched one step ahead using dead v220-231 as second register set
# speedup vs baseline: 1.0058x; 1.0038x over previous
; __device__ __forceinline__ void partialSM(f32x16& p0, f32x16& p1, float& m_reg, float& mn, float& alpha) {
;     ...
;     for (int r = 0; r < 16; ++r) p0[r] = p0[r] - mn;
; #pragma unroll
;     for (int r = 0; r < 16; ++r) p1[r] = p1[r] - mn;
; #pragma unroll
;     for (int r = 0; r < 16; ++r) p0[r] = __builtin_amdgcn_exp2f(p0[r]);
; __device__ __forceinline__ void qkt(f32x16& p0, f32x16& p1, const char* Ks, const bf16x8* qr, const char* qrl, int r32, int hi) {
;     p0 = f32x16{}; p1 = f32x16{};
; #pragma unroll
;     for (int d0 = 0; d0 < 12; ++d0) { const int cb = (d0 * 16 + hi * 8) * 2;
;         const bf16x8 b0 = *reinterpret_cast<const bf16x8*>(Ks + KSWZ(r32, cb));
;         const bf16x8 b1 = *reinterpret_cast<const bf16x8*>(Ks + KSWZ(32 + r32, cb));
;         const bf16x8 qq = d0 < QREG ? qr[d0 < QREG ? d0 : 0] : *reinterpret_cast<const bf16x8*>(qrl + (d0 - QREG) * 1024);
;         p0 = __builtin_amdgcn_mfma_f32_32x32x16_bf16(b0, qq, p0, 0, 0, 0);
;         p1 = __builtin_amdgcn_mfma_f32_32x32x16_bf16(b1, qq, p1, 0, 0, 0); }
.LBB0_1384:
	v_cndmask_b32_e64 v158, v136, v158, s[4:5]
	v_sub_f32_e32 v80, v80, v158
	v_sub_f32_e32 v81, v81, v158
	v_sub_f32_e32 v82, v82, v158
	v_sub_f32_e32 v83, v83, v158
	v_sub_f32_e32 v84, v84, v158
	v_sub_f32_e32 v85, v85, v158
	v_sub_f32_e32 v86, v86, v158
	v_sub_f32_e32 v87, v87, v158
	v_sub_f32_e32 v88, v88, v158
	v_sub_f32_e32 v89, v89, v158
	v_sub_f32_e32 v90, v90, v158
	v_sub_f32_e32 v91, v91, v158
	v_sub_f32_e32 v92, v92, v158
	v_sub_f32_e32 v93, v93, v158
	v_sub_f32_e32 v94, v94, v158
	v_sub_f32_e32 v95, v95, v158
	v_sub_f32_e32 v235, v68, v158
	v_sub_f32_e32 v236, v69, v158
	v_exp_f32_e32 v133, v80
	v_exp_f32_e32 v135, v81
	v_exp_f32_e32 v131, v82
	v_exp_f32_e32 v134, v83
	v_exp_f32_e32 v130, v84
	v_exp_f32_e32 v132, v85
	v_exp_f32_e32 v128, v86
	v_exp_f32_e32 v129, v87
	v_exp_f32_e32 v125, v88
	v_exp_f32_e32 v127, v89
	v_exp_f32_e32 v124, v90
	v_exp_f32_e32 v126, v91
	v_exp_f32_e32 v121, v92
	v_exp_f32_e32 v123, v93
	v_exp_f32_e32 v120, v94
	v_exp_f32_e32 v122, v95
	v_sub_f32_e32 v208, v64, v158
	v_sub_f32_e32 v209, v65, v158
	v_sub_f32_e32 v210, v66, v158
	v_sub_f32_e32 v211, v67, v158
	v_sub_f32_e32 v237, v70, v158
	v_sub_f32_e32 v238, v71, v158
	v_sub_f32_e32 v239, v72, v158
	v_sub_f32_e32 v240, v73, v158
	v_sub_f32_e32 v241, v74, v158
	v_sub_f32_e32 v242, v75, v158
	v_sub_f32_e32 v243, v76, v158
	v_sub_f32_e32 v244, v77, v158
	v_sub_f32_e32 v245, v78, v158
	v_sub_f32_e32 v246, v79, v158
	s_waitcnt lgkmcnt(0)
	s_barrier
	ds_read_b128 v[64:67], v184 offset:32768
	ds_read_b128 v[68:71], v184 offset:49152
	ds_read_b128 v[136:139], v186 offset:32768
	ds_read_b128 v[140:143], v186 offset:49152
	v_exp_f32_e32 v237, v237
	v_exp_f32_e32 v238, v238
	s_waitcnt lgkmcnt(3)
	v_mfma_f32_32x32x16_bf16 v[80:95], v[64:67], v[116:119], 0
	v_exp_f32_e32 v239, v239
	v_exp_f32_e32 v240, v240
	v_exp_f32_e32 v241, v241
	v_exp_f32_e32 v242, v242
	v_exp_f32_e32 v243, v243
	v_exp_f32_e32 v244, v244
	v_exp_f32_e32 v245, v245
	s_waitcnt lgkmcnt(2)
	v_mfma_f32_32x32x16_bf16 v[64:79], v[68:71], v[116:119], 0
	v_exp_f32_e32 v246, v246
	ds_read_b128 v[220:223], v188 offset:32768
	ds_read_b128 v[224:227], v188 offset:49152
	s_waitcnt lgkmcnt(2)
	v_mfma_f32_32x32x16_bf16 v[64:79], v[140:143], v[112:115], v[64:79]
	v_mfma_f32_32x32x16_bf16 v[80:95], v[136:139], v[112:115], v[80:95]
	ds_read_b128 v[136:139], v190 offset:32768
	ds_read_b128 v[140:143], v190 offset:49152
	s_waitcnt lgkmcnt(2)
	v_mfma_f32_32x32x16_bf16 v[64:79], v[224:227], v[108:111], v[64:79]
	v_mfma_f32_32x32x16_bf16 v[80:95], v[220:223], v[108:111], v[80:95]
	ds_read_b128 v[220:223], v192 offset:32768
	ds_read_b128 v[224:227], v192 offset:49152
	s_waitcnt lgkmcnt(2)
	v_mfma_f32_32x32x16_bf16 v[64:79], v[140:143], v[104:107], v[64:79]
	v_mfma_f32_32x32x16_bf16 v[80:95], v[136:139], v[104:107], v[80:95]
	ds_read_b128 v[136:139], v194 offset:32768
	ds_read_b128 v[140:143], v194 offset:49152
	s_waitcnt lgkmcnt(2)
	v_mfma_f32_32x32x16_bf16 v[64:79], v[224:227], v[100:103], v[64:79]
	v_mfma_f32_32x32x16_bf16 v[80:95], v[220:223], v[100:103], v[80:95]
	ds_read_b128 v[220:223], v196 offset:32768
	ds_read_b128 v[224:227], v196 offset:49152
	ds_read_b128 v[228:231], v177
	s_waitcnt lgkmcnt(3)
	v_mfma_f32_32x32x16_bf16 v[64:79], v[140:143], v[96:99], v[64:79]
	v_mfma_f32_32x32x16_bf16 v[80:95], v[136:139], v[96:99], v[80:95]
	ds_read_b128 v[136:139], v198 offset:32768
	ds_read_b128 v[140:143], v198 offset:49152
	ds_read_b128 v[144:147], v177 offset:1024
	s_waitcnt lgkmcnt(3)
	v_mfma_f32_32x32x16_bf16 v[64:79], v[224:227], v[228:231], v[64:79]
	v_mfma_f32_32x32x16_bf16 v[80:95], v[220:223], v[228:231], v[80:95]
	ds_read_b128 v[220:223], v200 offset:32768
	ds_read_b128 v[224:227], v200 offset:49152
	ds_read_b128 v[228:231], v177 offset:2048
	s_waitcnt lgkmcnt(3)
	v_mfma_f32_32x32x16_bf16 v[64:79], v[140:143], v[144:147], v[64:79]
	v_mfma_f32_32x32x16_bf16 v[80:95], v[136:139], v[144:147], v[80:95]
	ds_read_b128 v[136:139], v202 offset:32768
	ds_read_b128 v[140:143], v202 offset:49152
	ds_read_b128 v[144:147], v177 offset:3072
	s_waitcnt lgkmcnt(3)
	v_mfma_f32_32x32x16_bf16 v[64:79], v[224:227], v[228:231], v[64:79]
	v_mfma_f32_32x32x16_bf16 v[80:95], v[220:223], v[228:231], v[80:95]
	ds_read_b128 v[220:223], v204 offset:32768
	ds_read_b128 v[224:227], v204 offset:49152
	ds_read_b128 v[228:231], v177 offset:4096
	s_waitcnt lgkmcnt(3)
	v_mfma_f32_32x32x16_bf16 v[64:79], v[140:143], v[144:147], v[64:79]
	v_mfma_f32_32x32x16_bf16 v[80:95], v[136:139], v[144:147], v[80:95]
	ds_read_b128 v[136:139], v215 offset:32768
	ds_read_b128 v[140:143], v215 offset:49152
	ds_read_b128 v[144:147], v177 offset:5120
	s_waitcnt lgkmcnt(3)
	v_mfma_f32_32x32x16_bf16 v[64:79], v[224:227], v[228:231], v[64:79]
	v_mfma_f32_32x32x16_bf16 v[80:95], v[220:223], v[228:231], v[80:95]
	s_waitcnt lgkmcnt(0)
; __device__ __forceinline__ void partialSM(f32x16& p0, f32x16& p1, float& m_reg, float& mn, float& alpha) {
;     float pmax = p0[0];
; #pragma unroll
;     for (int r = 1; r < 16; ++r) pmax = fmaxf(pmax, p0[r]);
; #pragma unroll
;     for (int r = 0; r < 16; ++r) pmax = fmaxf(pmax, p1[r]);
;     { auto rr = __builtin_amdgcn_permlane32_swap(__float_as_uint(pmax), __float_as_uint(pmax), false, false); pmax = fmaxf(__uint_as_float(rr[0]), __uint_as_float(rr[1])); }
;     if (__builtin_expect(__all(pmax - m_reg <= THR2), 1)) { mn = m_reg; alpha = 1.f; }
;     else { mn = fmaxf(m_reg, pmax); alpha = __builtin_amdgcn_exp2f(m_reg - mn); m_reg = mn; }
; #pragma unroll
;     for (int r = 0; r < 16; ++r) p0[r] = p0[r] - mn;
; #pragma unroll
;     for (int r = 0; r < 16; ++r) p1[r] = p1[r] - mn;
; #pragma unroll
;     for (int r = 0; r < 16; ++r) p0[r] = __builtin_amdgcn_exp2f(p0[r]);
; }
; __device__ __forceinline__ void finishSM(f32x16& p0, f32x16& p1, float alpha, float& l_reg, bf16x8& pa0, bf16x8& pa1, bf16x8& pa2, bf16x8& pa3) {
; #pragma unroll
;     for (int r = 0; r < 16; ++r) p1[r] = __builtin_amdgcn_exp2f(p1[r]);
;     float ps = 0;
; #pragma unroll
;     for (int r = 0; r < 16; ++r) ps += p0[r];
; #pragma unroll
;     for (int r = 0; r < 16; ++r) ps += p1[r];
;     { auto rr = __builtin_amdgcn_permlane32_swap(__float_as_uint(ps), __float_as_uint(ps), false, false); ps = __uint_as_float(rr[0]) + __uint_as_float(rr[1]); }
;     l_reg = l_reg * alpha + ps;
;     ...
;     PK4(p0, 0, pa0); PK4(p0, 8, pa1); PK4(p1, 0, pa2); PK4(p1, 8, pa3);
;     ...
; }
; __device__ __forceinline__ void qkt(f32x16& p0, f32x16& p1, const char* Ks, const bf16x8* qr, const char* qrl, int r32, int hi) {
;     p0 = f32x16{}; p1 = f32x16{};
; #pragma unroll
;     for (int d0 = 0; d0 < 12; ++d0) { const int cb = (d0 * 16 + hi * 8) * 2;
;         const bf16x8 b0 = *reinterpret_cast<const bf16x8*>(Ks + KSWZ(r32, cb));
;         const bf16x8 b1 = *reinterpret_cast<const bf16x8*>(Ks + KSWZ(32 + r32, cb));
;         const bf16x8 qq = d0 < QREG ? qr[d0 < QREG ? d0 : 0] : *reinterpret_cast<const bf16x8*>(qrl + (d0 - QREG) * 1024);
;         p0 = __builtin_amdgcn_mfma_f32_32x32x16_bf16(b0, qq, p0, 0, 0, 0);
;         p1 = __builtin_amdgcn_mfma_f32_32x32x16_bf16(b1, qq, p1, 0, 0, 0); }
; }
	v_mfma_f32_32x32x16_bf16 v[64:79], v[140:143], v[144:147], v[64:79]
	v_add_f32_e32 v140, 0, v133
	v_add_f32_e32 v140, v135, v140
	v_add_f32_e32 v140, v131, v140
	v_add_f32_e32 v140, v134, v140
	v_add_f32_e32 v140, v130, v140
	v_add_f32_e32 v140, v132, v140
	v_add_f32_e32 v140, v128, v140
	v_add_f32_e32 v140, v129, v140
	v_add_f32_e32 v140, v125, v140
	v_add_f32_e32 v140, v127, v140
	v_add_f32_e32 v140, v124, v140
	v_add_f32_e32 v140, v126, v140
	v_mfma_f32_32x32x16_bf16 v[80:95], v[136:139], v[144:147], v[80:95]
	v_exp_f32_e32 v136, v208
	v_add_f32_e32 v140, v121, v140
	v_exp_f32_e32 v137, v209
	v_add_f32_e32 v140, v123, v140
	v_exp_f32_e32 v138, v210
	v_add_f32_e32 v140, v120, v140
	v_exp_f32_e32 v139, v211
	v_add_f32_e32 v140, v122, v140
	v_exp_f32_e32 v210, v235
	v_add_f32_e32 v140, v136, v140
	v_exp_f32_e32 v211, v236
	v_add_f32_e32 v140, v137, v140
	v_add_f32_e32 v140, v138, v140
	v_add_f32_e32 v140, v139, v140
	v_add_f32_e32 v140, v210, v140
	v_add_f32_e32 v140, v211, v140
	v_add_f32_e32 v140, v237, v140
	v_add_f32_e32 v140, v238, v140
	v_add_f32_e32 v140, v239, v140
	v_add_f32_e32 v140, v240, v140
	v_add_f32_e32 v140, v241, v140
	v_add_f32_e32 v140, v242, v140
	v_add_f32_e32 v140, v243, v140
	v_add_f32_e32 v140, v244, v140
	v_add_f32_e32 v140, v245, v140
	v_add_f32_e32 v235, v246, v140
	v_mov_b32_e32 v236, v235
	v_cvt_pk_bf16_f32 v140, v133, v135
	v_cvt_pk_bf16_f32 v141, v131, v134
	v_cvt_pk_bf16_f32 v142, v130, v132
	v_cvt_pk_bf16_f32 v143, v128, v129
	s_nop 1
	v_permlane32_swap_b32_e32 v235, v236
	v_permlane32_swap_b32_e32 v140, v142
	v_permlane32_swap_b32_e32 v141, v143
	v_cvt_pk_bf16_f32 v144, v125, v127
	v_cvt_pk_bf16_f32 v145, v124, v126
	v_cvt_pk_bf16_f32 v146, v121, v123
	v_cvt_pk_bf16_f32 v147, v120, v122
	v_cvt_pk_bf16_f32 v208, v136, v137
	v_cvt_pk_bf16_f32 v209, v138, v139
	v_cvt_pk_bf16_f32 v210, v210, v211
	v_cvt_pk_bf16_f32 v211, v237, v238
	v_cvt_pk_bf16_f32 v238, v239, v240
	v_cvt_pk_bf16_f32 v239, v241, v242
	v_cvt_pk_bf16_f32 v240, v243, v244
	v_cvt_pk_bf16_f32 v241, v245, v246
	s_nop 0
	v_permlane32_swap_b32_e32 v144, v146
	v_permlane32_swap_b32_e32 v145, v147
	v_permlane32_swap_b32_e32 v208, v210
	v_permlane32_swap_b32_e32 v209, v211
	v_permlane32_swap_b32_e32 v238, v240
	v_permlane32_swap_b32_e32 v239, v241
	s_mov_b32 s4, 0x234c0000
	v_add_co_u32_e32 v120, vcc, s4, v164
	s_mov_b32 s4, 0x234e0000
	s_nop 0
	v_addc_co_u32_e32 v121, vcc, 0, v165, vcc
	v_add_co_u32_e32 v124, vcc, s4, v164
	s_nop 1
	v_addc_co_u32_e32 v125, vcc, 0, v165, vcc
	v_add_co_u32_e32 v128, vcc, s95, v166
	global_load_dwordx4 v[120:123], v[120:121], off
	s_nop 0
	global_load_dwordx4 v[124:127], v[124:125], off
	v_addc_co_u32_e32 v129, vcc, 0, v167, vcc
	v_add_co_u32_e32 v132, vcc, s95, v168
	s_nop 1
	v_addc_co_u32_e32 v133, vcc, 0, v169, vcc
	v_add_co_u32_e32 v136, vcc, s95, v170
	global_load_dwordx4 v[128:131], v[128:129], off
	s_nop 0
	global_load_dwordx4 v[132:135], v[132:133], off
	v_addc_co_u32_e32 v137, vcc, 0, v171, vcc
	global_load_dwordx4 v[136:139], v[136:137], off
	ds_read_b64_tr_b16 v[164:165], v175 offset:0
	ds_read_b64_tr_b16 v[166:167], v175 offset:0x800
	ds_read_b64_tr_b16 v[168:169], v175 offset:0x1000
	ds_read_b64_tr_b16 v[170:171], v175 offset:0x1800
	ds_read_b64_tr_b16 v[242:243], v175 offset:0x2000
	ds_read_b64_tr_b16 v[244:245], v175 offset:0x2800
	ds_read_b64_tr_b16 v[246:247], v175 offset:0x3000
	ds_read_b64_tr_b16 v[248:249], v175 offset:0x3800
	s_waitcnt lgkmcnt(0)
	s_nop 0
	v_mfma_f32_32x32x16_bf16 v[0:15], v[140:143], v[164:167], v[0:15]
	ds_read_b64_tr_b16 v[164:165], v175 offset:0x200
	ds_read_b64_tr_b16 v[166:167], v175 offset:0xa00
	v_mfma_f32_32x32x16_bf16 v[0:15], v[144:147], v[168:171], v[0:15]
	ds_read_b64_tr_b16 v[168:169], v175 offset:0x1200
	ds_read_b64_tr_b16 v[170:171], v175 offset:0x1a00
	v_mfma_f32_32x32x16_bf16 v[0:15], v[208:211], v[242:245], v[0:15]
	ds_read_b64_tr_b16 v[242:243], v175 offset:0x2200
	ds_read_b64_tr_b16 v[244:245], v175 offset:0x2a00
	v_mfma_f32_32x32x16_bf16 v[0:15], v[238:241], v[246:249], v[0:15]
	ds_read_b64_tr_b16 v[246:247], v175 offset:0x3200
	ds_read_b64_tr_b16 v[248:249], v175 offset:0x3a00
	s_waitcnt lgkmcnt(0)
	v_mfma_f32_32x32x16_bf16 v[48:63], v[140:143], v[164:167], v[48:63]
	ds_read_b64_tr_b16 v[164:165], v175 offset:0x400
	ds_read_b64_tr_b16 v[166:167], v175 offset:0xc00
	v_mfma_f32_32x32x16_bf16 v[48:63], v[144:147], v[168:171], v[48:63]
	ds_read_b64_tr_b16 v[168:169], v175 offset:0x1400
	ds_read_b64_tr_b16 v[170:171], v175 offset:0x1c00
	v_mfma_f32_32x32x16_bf16 v[48:63], v[208:211], v[242:245], v[48:63]
	ds_read_b64_tr_b16 v[242:243], v175 offset:0x2400
	ds_read_b64_tr_b16 v[244:245], v175 offset:0x2c00
	v_mfma_f32_32x32x16_bf16 v[48:63], v[238:241], v[246:249], v[48:63]
	ds_read_b64_tr_b16 v[246:247], v175 offset:0x3400
	ds_read_b64_tr_b16 v[248:249], v175 offset:0x3c00
	s_waitcnt lgkmcnt(0)
	v_mfma_f32_32x32x16_bf16 v[32:47], v[140:143], v[164:167], v[32:47]
	ds_read_b64_tr_b16 v[164:165], v175 offset:0x600
	ds_read_b64_tr_b16 v[166:167], v175 offset:0xe00
	v_mfma_f32_32x32x16_bf16 v[32:47], v[144:147], v[168:171], v[32:47]
	ds_read_b64_tr_b16 v[168:169], v175 offset:0x1600
	ds_read_b64_tr_b16 v[170:171], v175 offset:0x1e00
	v_mfma_f32_32x32x16_bf16 v[32:47], v[208:211], v[242:245], v[32:47]
	ds_read_b64_tr_b16 v[242:243], v175 offset:0x2600
	ds_read_b64_tr_b16 v[244:245], v175 offset:0x2e00
	v_mfma_f32_32x32x16_bf16 v[32:47], v[238:241], v[246:249], v[32:47]
	ds_read_b64_tr_b16 v[246:247], v175 offset:0x3600
	ds_read_b64_tr_b16 v[248:249], v175 offset:0x3e00
	s_waitcnt lgkmcnt(0)
	v_mfma_f32_32x32x16_bf16 v[16:31], v[140:143], v[164:167], v[16:31]
	v_max_f32_e32 v140, v81, v81
	v_max_f32_e32 v141, v80, v80
	v_max_f32_e32 v140, v141, v140
	v_max3_f32 v140, v140, v82, v83
	v_max3_f32 v140, v140, v84, v85
	v_max3_f32 v140, v140, v86, v87
	v_max3_f32 v140, v140, v88, v89
	v_max3_f32 v140, v140, v90, v91
	v_mfma_f32_32x32x16_bf16 v[16:31], v[144:147], v[168:171], v[16:31]
	v_max3_f32 v140, v140, v92, v93
	v_max3_f32 v140, v140, v94, v95
	v_max3_f32 v140, v140, v64, v65
	v_max3_f32 v140, v140, v66, v67
	v_max3_f32 v140, v140, v68, v69
	v_max3_f32 v140, v140, v70, v71
	v_max3_f32 v140, v140, v72, v73
	v_max3_f32 v140, v140, v74, v75
	v_mfma_f32_32x32x16_bf16 v[16:31], v[208:211], v[242:245], v[16:31]
	v_max3_f32 v140, v140, v76, v77
	v_max3_f32 v140, v140, v78, v79
	v_mov_b32_e32 v141, v140
	s_nop 1
	v_permlane32_swap_b32_e32 v140, v141
	v_max_f32_e32 v141, v141, v141
	v_max_f32_e32 v140, v140, v140
	v_max_f32_e32 v140, v140, v141
	v_sub_f32_e32 v141, v140, v158
	v_cmp_ge_f32_e32 vcc, s62, v141
	v_max_f32_e32 v141, v158, v158
	v_mfma_f32_32x32x16_bf16 v[16:31], v[238:241], v[246:249], v[16:31]
	v_max_f32_e32 v141, v141, v140
	v_sub_f32_e32 v140, v158, v141
	v_exp_f32_e32 v140, v140
	s_cmp_eq_u64 vcc, exec
	s_cselect_b64 s[4:5], -1, 0
	s_barrier
; #define SWRITE(b) do { *(bf16x8*)(V_lds + (b) * SHM_V + vst0) = vs0; *(bf16x8*)(V_lds + (b) * SHM_V + vst1) = vs1; \
;     *(bf16x8*)(K_lds + (b) * SHM_K + KSWZ(kr0, kc0 * 16)) = ks0; *(bf16x8*)(K_lds + (b) * SHM_K + KSWZ(kr1, kc1 * 16)) = ks1; *(bf16x8*)(K_lds + (b) * SHM_K + KSWZ(kr2, kc2 * 16)) = ks2; } while (0)
; #define SWAIT() asm volatile("s_waitcnt vmcnt(0)" ::: "memory")
; #define RESC(a) do { if (__any((a) < 1.f)) { if (hi == 0) al_l[r32] = (a); asm volatile("s_waitcnt lgkmcnt(0)" ::: "memory"); \
;     _Pragma("unroll") for (int d = 0; d < 4; ++d) _Pragma("unroll") for (int r = 0; r < 16; ++r) o[d][r] *= al_l[crow(r, hi)]; } } while (0)
; __device__ __forceinline__ void attn_unit(const bf16_t* __restrict__ Qb, const bf16_t* __restrict__ Kh, const bf16_t* __restrict__ Vh, bf16_t* __restrict__ Ob, int seq, char* lds) {
;     ...
;         __syncthreads(); SWAIT(); SWRITE(0);
;         RESC(alB); __syncthreads();
	s_waitcnt vmcnt(0)
	v_cndmask_b32_e64 v140, v140, 1.0, s[4:5]
	v_cmp_gt_f32_e32 vcc, 1.0, v140
	s_waitcnt vmcnt(4)
	ds_write_b128 v178, v[120:123] offset:16384
	s_waitcnt vmcnt(3)
	ds_write_b128 v179, v[124:127] offset:16384
	s_waitcnt vmcnt(2)
	ds_write_b128 v216, v[128:131]
	s_waitcnt vmcnt(1)
	ds_write_b128 v217, v[132:135]
	s_waitcnt vmcnt(0)
	ds_write_b128 v218, v[136:139]
	s_cbranch_vccz .LBB0_1388
	s_and_saveexec_b64 s[12:13], s[2:3]
	ds_write_b32 v173, v140 offset:128
	s_or_b64 exec, exec, s[12:13]
	s_waitcnt lgkmcnt(0)
	v_add_u32_e32 v132, v149, v160
	ds_read_b128 v[120:123], v132 offset:224
	ds_read_b128 v[124:127], v132 offset:192
	ds_read_b128 v[128:131], v132 offset:160
	ds_read_b128 v[132:135], v132 offset:128
	s_waitcnt lgkmcnt(3)
	v_pk_mul_f32 v[12:13], v[12:13], v[120:121]
	s_waitcnt lgkmcnt(2)
	v_pk_mul_f32 v[8:9], v[8:9], v[124:125]
	s_waitcnt lgkmcnt(1)
	v_pk_mul_f32 v[4:5], v[4:5], v[128:129]
	v_pk_mul_f32 v[14:15], v[14:15], v[122:123]
	v_pk_mul_f32 v[10:11], v[10:11], v[126:127]
	v_pk_mul_f32 v[6:7], v[6:7], v[130:131]
	s_waitcnt lgkmcnt(0)
	v_pk_mul_f32 v[2:3], v[2:3], v[134:135]
	v_pk_mul_f32 v[0:1], v[0:1], v[132:133]
	v_pk_mul_f32 v[60:61], v[60:61], v[120:121]
	v_pk_mul_f32 v[56:57], v[56:57], v[124:125]
	v_pk_mul_f32 v[52:53], v[52:53], v[128:129]
	v_pk_mul_f32 v[62:63], v[62:63], v[122:123]
	v_pk_mul_f32 v[58:59], v[58:59], v[126:127]
	v_pk_mul_f32 v[54:55], v[54:55], v[130:131]
	v_pk_mul_f32 v[50:51], v[50:51], v[134:135]
	v_pk_mul_f32 v[48:49], v[48:49], v[132:133]
	v_pk_mul_f32 v[44:45], v[44:45], v[120:121]
	v_pk_mul_f32 v[40:41], v[40:41], v[124:125]
	v_pk_mul_f32 v[36:37], v[36:37], v[128:129]
	v_pk_mul_f32 v[46:47], v[46:47], v[122:123]
	v_pk_mul_f32 v[42:43], v[42:43], v[126:127]
	v_pk_mul_f32 v[38:39], v[38:39], v[130:131]
	v_pk_mul_f32 v[34:35], v[34:35], v[134:135]
	v_pk_mul_f32 v[32:33], v[32:33], v[132:133]
	v_pk_mul_f32 v[28:29], v[28:29], v[120:121]
	v_pk_mul_f32 v[24:25], v[24:25], v[124:125]
	v_pk_mul_f32 v[20:21], v[20:21], v[128:129]
	v_pk_mul_f32 v[30:31], v[30:31], v[122:123]
	v_pk_mul_f32 v[26:27], v[26:27], v[126:127]
	v_pk_mul_f32 v[22:23], v[22:23], v[130:131]
	v_pk_mul_f32 v[18:19], v[18:19], v[134:135]
	v_pk_mul_f32 v[16:17], v[16:17], v[132:133]

; #define SBAR() __builtin_amdgcn_sched_barrier(0)
; __device__ __forceinline__ void finishSM(f32x16& p0, f32x16& p1, float alpha, float& l_reg, bf16x8& pa0, bf16x8& pa1, bf16x8& pa2, bf16x8& pa3) {
; #pragma unroll
;     for (int r = 0; r < 16; ++r) p1[r] = __builtin_amdgcn_exp2f(p1[r]);
;     float ps = 0;
; #pragma unroll
;     for (int r = 0; r < 16; ++r) ps += p0[r];
; #pragma unroll
;     for (int r = 0; r < 16; ++r) ps += p1[r];
;     { auto rr = __builtin_amdgcn_permlane32_swap(__float_as_uint(ps), __float_as_uint(ps), false, false); ps = __uint_as_float(rr[0]) + __uint_as_float(rr[1]); }
;     l_reg = l_reg * alpha + ps;
;     ...
;     PK4(p0, 0, pa0); PK4(p0, 8, pa1); PK4(p1, 0, pa2); PK4(p1, 8, pa3);
;     ...
; }
; __device__ __forceinline__ void qkt(f32x16& p0, f32x16& p1, const char* Ks, const bf16x8* qr, const char* qrl, int r32, int hi) {
;     p0 = f32x16{}; p1 = f32x16{};
; #pragma unroll
;     for (int d0 = 0; d0 < 12; ++d0) { const int cb = (d0 * 16 + hi * 8) * 2;
;         const bf16x8 b0 = *reinterpret_cast<const bf16x8*>(Ks + KSWZ(r32, cb));
;         const bf16x8 b1 = *reinterpret_cast<const bf16x8*>(Ks + KSWZ(32 + r32, cb));
;         const bf16x8 qq = d0 < QREG ? qr[d0 < QREG ? d0 : 0] : *reinterpret_cast<const bf16x8*>(qrl + (d0 - QREG) * 1024);
;         p0 = __builtin_amdgcn_mfma_f32_32x32x16_bf16(b0, qq, p0, 0, 0, 0);
;         p1 = __builtin_amdgcn_mfma_f32_32x32x16_bf16(b1, qq, p1, 0, 0, 0); }
; __device__ __forceinline__ void attn_unit(const bf16_t* __restrict__ Qb, const bf16_t* __restrict__ Kh, const bf16_t* __restrict__ Vh, bf16_t* __restrict__ Ob, int seq, char* lds) {
;     ...
;     SBAR(); qkt(pB0, pB1, K_lds + SHM_K, qr, qrl, r32, hi);
;     finishSM(pA0, pA1, alA, l_reg, pa0, pa1, pa2, pa3); SBAR();
;     pv_d0(o, vb0, pa0, pa1, pa2, pa3); partialSM(pB0, pB1, m_reg, mnB, alB);
.LBB0_1391:
	v_add_u32_e32 v220, s14, v183
	v_add_u32_e32 v221, s14, v185
	v_add_u32_e32 v222, s14, v187
	v_add_u32_e32 v223, s14, v189
	v_add_u32_e32 v224, s14, v191
	v_add_u32_e32 v225, s14, v193
	v_add_u32_e32 v226, s14, v195
	v_add_u32_e32 v227, s14, v197
	v_add_u32_e32 v229, s14, v199
	v_add_u32_e32 v228, s14, v201
	v_add_u32_e32 v230, s14, v203
	v_add_u32_e32 v231, s14, v205
	ds_read_b128 v[64:67], v220
	ds_read_b128 v[68:71], v220 offset:16384
	s_waitcnt lgkmcnt(1)
	v_mfma_f32_32x32x16_bf16 v[80:95], v[64:67], v[116:119], 0
	s_waitcnt lgkmcnt(0)
	v_mfma_f32_32x32x16_bf16 v[64:79], v[68:71], v[116:119], 0
	ds_read_b128 v[116:119], v221
	ds_read_b128 v[150:153], v221 offset:16384
	s_waitcnt lgkmcnt(1)
	v_mfma_f32_32x32x16_bf16 v[80:95], v[116:119], v[112:115], v[80:95]
	s_waitcnt lgkmcnt(0)
	v_mfma_f32_32x32x16_bf16 v[64:79], v[150:153], v[112:115], v[64:79]
	ds_read_b128 v[112:115], v222
	ds_read_b128 v[116:119], v222 offset:16384
	s_waitcnt lgkmcnt(1)
	v_mfma_f32_32x32x16_bf16 v[80:95], v[112:115], v[108:111], v[80:95]
	s_waitcnt lgkmcnt(0)
	v_mfma_f32_32x32x16_bf16 v[64:79], v[116:119], v[108:111], v[64:79]
	ds_read_b128 v[108:111], v223
	ds_read_b128 v[112:115], v223 offset:16384
	v_exp_f32_e32 v116, v130
	v_exp_f32_e32 v117, v131
	v_exp_f32_e32 v118, v120
	v_exp_f32_e32 v119, v121
	v_exp_f32_e32 v120, v128
	v_exp_f32_e32 v121, v129
	s_waitcnt lgkmcnt(1)
	v_mfma_f32_32x32x16_bf16 v[80:95], v[108:111], v[104:107], v[80:95]
	s_waitcnt lgkmcnt(0)
	v_mfma_f32_32x32x16_bf16 v[64:79], v[112:115], v[104:107], v[64:79]
	ds_read_b128 v[104:107], v224
	ds_read_b128 v[108:111], v224 offset:16384
	v_exp_f32_e32 v112, v124
	v_exp_f32_e32 v113, v125
	v_exp_f32_e32 v114, v126
	v_exp_f32_e32 v115, v127
	s_waitcnt lgkmcnt(1)
	v_mfma_f32_32x32x16_bf16 v[80:95], v[104:107], v[100:103], v[80:95]
	s_waitcnt lgkmcnt(0)
	v_mfma_f32_32x32x16_bf16 v[64:79], v[108:111], v[100:103], v[64:79]
	ds_read_b128 v[100:103], v225
	ds_read_b128 v[104:107], v225 offset:16384
	v_exp_f32_e32 v108, v134
	v_exp_f32_e32 v109, v135
	v_exp_f32_e32 v110, v122
	v_exp_f32_e32 v111, v123
	s_waitcnt lgkmcnt(1)
	v_mfma_f32_32x32x16_bf16 v[80:95], v[100:103], v[96:99], v[80:95]
	s_waitcnt lgkmcnt(0)
	v_mfma_f32_32x32x16_bf16 v[64:79], v[104:107], v[96:99], v[64:79]
	ds_read_b128 v[96:99], v226
	ds_read_b128 v[100:103], v226 offset:16384
	ds_read_b128 v[104:107], v177
	s_waitcnt lgkmcnt(0)
	v_mfma_f32_32x32x16_bf16 v[80:95], v[96:99], v[104:107], v[80:95]
	v_mfma_f32_32x32x16_bf16 v[64:79], v[100:103], v[104:107], v[64:79]
	ds_read_b128 v[96:99], v227
	ds_read_b128 v[100:103], v227 offset:16384
	ds_read_b128 v[104:107], v177 offset:1024
	s_waitcnt lgkmcnt(0)
	v_mfma_f32_32x32x16_bf16 v[80:95], v[96:99], v[104:107], v[80:95]
	v_mfma_f32_32x32x16_bf16 v[64:79], v[100:103], v[104:107], v[64:79]
	ds_read_b128 v[96:99], v229
	ds_read_b128 v[100:103], v229 offset:16384
	ds_read_b128 v[104:107], v177 offset:2048
	s_waitcnt lgkmcnt(0)
	v_mfma_f32_32x32x16_bf16 v[80:95], v[96:99], v[104:107], v[80:95]
	v_mfma_f32_32x32x16_bf16 v[64:79], v[100:103], v[104:107], v[64:79]
	ds_read_b128 v[96:99], v228
	ds_read_b128 v[100:103], v228 offset:16384
	ds_read_b128 v[104:107], v177 offset:3072
	s_waitcnt lgkmcnt(0)
	v_mfma_f32_32x32x16_bf16 v[80:95], v[96:99], v[104:107], v[80:95]
	v_mfma_f32_32x32x16_bf16 v[64:79], v[100:103], v[104:107], v[64:79]
	ds_read_b128 v[96:99], v230
	ds_read_b128 v[100:103], v230 offset:16384
	ds_read_b128 v[104:107], v177 offset:4096
	s_waitcnt lgkmcnt(0)
	v_mfma_f32_32x32x16_bf16 v[80:95], v[96:99], v[104:107], v[80:95]
	v_mfma_f32_32x32x16_bf16 v[64:79], v[100:103], v[104:107], v[64:79]
	ds_read_b128 v[96:99], v231
	ds_read_b128 v[100:103], v231 offset:16384
	ds_read_b128 v[104:107], v177 offset:5120
	s_waitcnt lgkmcnt(0)
	v_mfma_f32_32x32x16_bf16 v[80:95], v[96:99], v[104:107], v[80:95]
	v_add_f32_e32 v96, 0, v136
	v_add_f32_e32 v96, v166, v96
	v_add_f32_e32 v96, v137, v96
	v_add_f32_e32 v96, v167, v96
	v_add_f32_e32 v96, v138, v96
	v_add_f32_e32 v96, v168, v96
	v_add_f32_e32 v96, v139, v96
	v_add_f32_e32 v96, v165, v96
	v_add_f32_e32 v96, v144, v96
	v_add_f32_e32 v96, v146, v96
	v_add_f32_e32 v96, v145, v96
	v_add_f32_e32 v96, v164, v96
	v_mfma_f32_32x32x16_bf16 v[64:79], v[100:103], v[104:107], v[64:79]
	v_exp_f32_e32 v106, v132
	v_add_f32_e32 v96, v141, v96
	v_exp_f32_e32 v107, v133
	v_add_f32_e32 v96, v143, v96
	v_add_f32_e32 v96, v142, v96
	v_add_f32_e32 v96, v147, v96
	v_add_f32_e32 v96, v106, v96
	v_add_f32_e32 v96, v107, v96
	v_add_f32_e32 v96, v108, v96
	v_add_f32_e32 v96, v109, v96
	v_add_f32_e32 v96, v110, v96
	v_add_f32_e32 v96, v111, v96
	v_add_f32_e32 v96, v112, v96
	v_add_f32_e32 v96, v113, v96
	v_add_f32_e32 v96, v114, v96
	v_add_f32_e32 v96, v115, v96
	v_add_f32_e32 v96, v116, v96
	v_add_f32_e32 v96, v117, v96
	v_add_f32_e32 v96, v118, v96
	v_add_f32_e32 v96, v119, v96
	v_add_f32_e32 v96, v120, v96
	v_add_f32_e32 v96, v121, v96
	v_mov_b32_e32 v97, v96
	v_cvt_pk_bf16_f32 v98, v136, v166
	v_cvt_pk_bf16_f32 v99, v137, v167
	v_cvt_pk_bf16_f32 v100, v138, v168
	v_cvt_pk_bf16_f32 v101, v139, v165
	s_nop 1
	v_permlane32_swap_b32_e32 v96, v97
	v_permlane32_swap_b32_e32 v98, v100
	v_permlane32_swap_b32_e32 v99, v101
	v_cvt_pk_bf16_f32 v102, v144, v146
	v_cvt_pk_bf16_f32 v103, v145, v164
	v_cvt_pk_bf16_f32 v104, v141, v143
	v_cvt_pk_bf16_f32 v105, v142, v147
	v_cvt_pk_bf16_f32 v106, v106, v107
	v_cvt_pk_bf16_f32 v107, v108, v109
	v_cvt_pk_bf16_f32 v108, v110, v111
	v_cvt_pk_bf16_f32 v109, v112, v113
	v_cvt_pk_bf16_f32 v110, v114, v115
	v_cvt_pk_bf16_f32 v111, v116, v117
	v_cvt_pk_bf16_f32 v112, v118, v119
	v_cvt_pk_bf16_f32 v113, v120, v121
	s_nop 0
	v_permlane32_swap_b32_e32 v102, v104
	v_permlane32_swap_b32_e32 v103, v105
	v_permlane32_swap_b32_e32 v106, v108
	v_permlane32_swap_b32_e32 v107, v109
	v_permlane32_swap_b32_e32 v110, v112
	v_permlane32_swap_b32_e32 v111, v113
	ds_read_b64_tr_b16 v[114:115], v176 offset:0
	ds_read_b64_tr_b16 v[116:117], v176 offset:0x800
	ds_read_b64_tr_b16 v[118:119], v176 offset:0x1000
	ds_read_b64_tr_b16 v[120:121], v176 offset:0x1800
	ds_read_b64_tr_b16 v[122:123], v176 offset:0x2000
	ds_read_b64_tr_b16 v[124:125], v176 offset:0x2800
	ds_read_b64_tr_b16 v[126:127], v176 offset:0x3000
	ds_read_b64_tr_b16 v[128:129], v176 offset:0x3800
	s_waitcnt lgkmcnt(0)
; __device__ __forceinline__ void partialSM(f32x16& p0, f32x16& p1, float& m_reg, float& mn, float& alpha) {
;     float pmax = p0[0];
; #pragma unroll
;     for (int r = 1; r < 16; ++r) pmax = fmaxf(pmax, p0[r]);
; #pragma unroll
;     for (int r = 0; r < 16; ++r) pmax = fmaxf(pmax, p1[r]);
;     { auto rr = __builtin_amdgcn_permlane32_swap(__float_as_uint(pmax), __float_as_uint(pmax), false, false); pmax = fmaxf(__uint_as_float(rr[0]), __uint_as_float(rr[1])); }
;     if (__builtin_expect(__all(pmax - m_reg <= THR2), 1)) { mn = m_reg; alpha = 1.f; }
;     else { mn = fmaxf(m_reg, pmax); alpha = __builtin_amdgcn_exp2f(m_reg - mn); m_reg = mn; }
; #pragma unroll
;     for (int r = 0; r < 16; ++r) p0[r] = p0[r] - mn;
; #pragma unroll
;     for (int r = 0; r < 16; ++r) p1[r] = p1[r] - mn;
; #pragma unroll
;     for (int r = 0; r < 16; ++r) p0[r] = __builtin_amdgcn_exp2f(p0[r]);
; }
; __device__ __forceinline__ void finishSM(f32x16& p0, f32x16& p1, float alpha, float& l_reg, bf16x8& pa0, bf16x8& pa1, bf16x8& pa2, bf16x8& pa3) {
; #pragma unroll
;     for (int r = 0; r < 16; ++r) p1[r] = __builtin_amdgcn_exp2f(p1[r]);
;     float ps = 0;
; #pragma unroll
;     for (int r = 0; r < 16; ++r) ps += p0[r];
; #pragma unroll
;     for (int r = 0; r < 16; ++r) ps += p1[r];
;     { auto rr = __builtin_amdgcn_permlane32_swap(__float_as_uint(ps), __float_as_uint(ps), false, false); ps = __uint_as_float(rr[0]) + __uint_as_float(rr[1]); }
;     l_reg = l_reg * alpha + ps;
;     ...
;     PK4(p0, 0, pa0); PK4(p0, 8, pa1); PK4(p1, 0, pa2); PK4(p1, 8, pa3);
;     ...
; }
; __device__ __forceinline__ void qkt(f32x16& p0, f32x16& p1, const char* Ks, const bf16x8* qr, const char* qrl, int r32, int hi) {
;     p0 = f32x16{}; p1 = f32x16{};
; #pragma unroll
;     for (int d0 = 0; d0 < 12; ++d0) { const int cb = (d0 * 16 + hi * 8) * 2;
;         const bf16x8 b0 = *reinterpret_cast<const bf16x8*>(Ks + KSWZ(r32, cb));
;         const bf16x8 b1 = *reinterpret_cast<const bf16x8*>(Ks + KSWZ(32 + r32, cb));
;         const bf16x8 qq = d0 < QREG ? qr[d0 < QREG ? d0 : 0] : *reinterpret_cast<const bf16x8*>(qrl + (d0 - QREG) * 1024);
;         p0 = __builtin_amdgcn_mfma_f32_32x32x16_bf16(b0, qq, p0, 0, 0, 0);
;         p1 = __builtin_amdgcn_mfma_f32_32x32x16_bf16(b1, qq, p1, 0, 0, 0); }
; }
	s_nop 0
	v_mfma_f32_32x32x16_bf16 v[0:15], v[98:101], v[114:117], v[0:15]
	ds_read_b64_tr_b16 v[114:115], v176 offset:0x200
	ds_read_b64_tr_b16 v[116:117], v176 offset:0xa00
	v_mfma_f32_32x32x16_bf16 v[0:15], v[102:105], v[118:121], v[0:15]
	ds_read_b64_tr_b16 v[118:119], v176 offset:0x1200
	ds_read_b64_tr_b16 v[120:121], v176 offset:0x1a00
	v_mfma_f32_32x32x16_bf16 v[0:15], v[106:109], v[122:125], v[0:15]
	ds_read_b64_tr_b16 v[122:123], v176 offset:0x2200
	ds_read_b64_tr_b16 v[124:125], v176 offset:0x2a00
	v_mfma_f32_32x32x16_bf16 v[0:15], v[110:113], v[126:129], v[0:15]
	ds_read_b64_tr_b16 v[126:127], v176 offset:0x3200
	ds_read_b64_tr_b16 v[128:129], v176 offset:0x3a00
	s_waitcnt lgkmcnt(0)
	v_mfma_f32_32x32x16_bf16 v[48:63], v[98:101], v[114:117], v[48:63]
	ds_read_b64_tr_b16 v[114:115], v176 offset:0x400
	ds_read_b64_tr_b16 v[116:117], v176 offset:0xc00
	v_mfma_f32_32x32x16_bf16 v[48:63], v[102:105], v[118:121], v[48:63]
	ds_read_b64_tr_b16 v[118:119], v176 offset:0x1400
	ds_read_b64_tr_b16 v[120:121], v176 offset:0x1c00
	v_mfma_f32_32x32x16_bf16 v[48:63], v[106:109], v[122:125], v[48:63]
	ds_read_b64_tr_b16 v[122:123], v176 offset:0x2400
	ds_read_b64_tr_b16 v[124:125], v176 offset:0x2c00
	v_mfma_f32_32x32x16_bf16 v[48:63], v[110:113], v[126:129], v[48:63]
	ds_read_b64_tr_b16 v[126:127], v176 offset:0x3400
	ds_read_b64_tr_b16 v[128:129], v176 offset:0x3c00
	s_waitcnt lgkmcnt(0)
	v_mfma_f32_32x32x16_bf16 v[32:47], v[98:101], v[114:117], v[32:47]
	ds_read_b64_tr_b16 v[114:115], v176 offset:0x600
	ds_read_b64_tr_b16 v[116:117], v176 offset:0xe00
	v_mfma_f32_32x32x16_bf16 v[32:47], v[102:105], v[118:121], v[32:47]
	ds_read_b64_tr_b16 v[118:119], v176 offset:0x1600
	ds_read_b64_tr_b16 v[120:121], v176 offset:0x1e00
	v_mfma_f32_32x32x16_bf16 v[32:47], v[106:109], v[122:125], v[32:47]
	ds_read_b64_tr_b16 v[122:123], v176 offset:0x2600
	ds_read_b64_tr_b16 v[124:125], v176 offset:0x2e00
	v_mfma_f32_32x32x16_bf16 v[32:47], v[110:113], v[126:129], v[32:47]
	ds_read_b64_tr_b16 v[126:127], v176 offset:0x3600
	ds_read_b64_tr_b16 v[128:129], v176 offset:0x3e00
	s_waitcnt lgkmcnt(0)
	v_mfma_f32_32x32x16_bf16 v[16:31], v[98:101], v[114:117], v[16:31]
	v_max_f32_e32 v98, v81, v81
	v_max_f32_e32 v99, v80, v80
	v_max_f32_e32 v98, v99, v98
	v_max3_f32 v98, v98, v82, v83
	v_max3_f32 v98, v98, v84, v85
	v_max3_f32 v98, v98, v86, v87
	v_max3_f32 v98, v98, v88, v89
	v_max3_f32 v98, v98, v90, v91
	v_mfma_f32_32x32x16_bf16 v[16:31], v[102:105], v[118:121], v[16:31]
	v_max3_f32 v98, v98, v92, v93
	v_max3_f32 v98, v98, v94, v95
	v_max3_f32 v98, v98, v64, v65
	v_max3_f32 v98, v98, v66, v67
	v_max3_f32 v98, v98, v68, v69
	v_max3_f32 v98, v98, v70, v71
	v_max3_f32 v98, v98, v72, v73
	v_max3_f32 v98, v98, v74, v75
	v_mfma_f32_32x32x16_bf16 v[16:31], v[106:109], v[122:125], v[16:31]
	v_max3_f32 v98, v98, v76, v77
	v_max3_f32 v98, v98, v78, v79
	v_mov_b32_e32 v99, v98
	s_nop 1
	v_permlane32_swap_b32_e32 v98, v99
	v_max_f32_e32 v99, v99, v99
	v_max_f32_e32 v98, v98, v98
	v_max_f32_e32 v98, v98, v99
	v_sub_f32_e32 v99, v98, v158
	v_cmp_ge_f32_e32 vcc, s62, v99
	v_max_f32_e32 v99, v158, v158
	v_mfma_f32_32x32x16_bf16 v[16:31], v[110:113], v[126:129], v[16:31]
	v_max_f32_e32 v99, v99, v98
	v_sub_f32_e32 v98, v158, v99
	v_exp_f32_e32 v98, v98
	s_cmp_eq_u64 vcc, exec
	s_cselect_b64 s[4:5], -1, 0
	v_cndmask_b32_e64 v98, v98, 1.0, s[4:5]
	v_cmp_gt_f32_e32 vcc, 1.0, v98
	s_barrier
	s_cbranch_vccz .LBB0_1395
	s_and_saveexec_b64 s[12:13], s[2:3]
	ds_write_b32 v173, v98 offset:128
	s_or_b64 exec, exec, s[12:13]
	s_waitcnt lgkmcnt(0)
	v_add_u32_e32 v112, v149, v160
	ds_read_b128 v[100:103], v112 offset:224
	ds_read_b128 v[104:107], v112 offset:192
	ds_read_b128 v[108:111], v112 offset:160
	ds_read_b128 v[112:115], v112 offset:128
	s_waitcnt lgkmcnt(3)
	v_pk_mul_f32 v[12:13], v[12:13], v[100:101]
	s_waitcnt lgkmcnt(2)
	v_pk_mul_f32 v[8:9], v[8:9], v[104:105]
	s_waitcnt lgkmcnt(1)
	v_pk_mul_f32 v[4:5], v[4:5], v[108:109]
	v_pk_mul_f32 v[14:15], v[14:15], v[102:103]
	v_pk_mul_f32 v[10:11], v[10:11], v[106:107]
	v_pk_mul_f32 v[6:7], v[6:7], v[110:111]
	s_waitcnt lgkmcnt(0)
	v_pk_mul_f32 v[2:3], v[2:3], v[114:115]
	v_pk_mul_f32 v[0:1], v[0:1], v[112:113]
	v_pk_mul_f32 v[60:61], v[60:61], v[100:101]
	v_pk_mul_f32 v[56:57], v[56:57], v[104:105]
	v_pk_mul_f32 v[52:53], v[52:53], v[108:109]
	v_pk_mul_f32 v[62:63], v[62:63], v[102:103]
	v_pk_mul_f32 v[58:59], v[58:59], v[106:107]
	v_pk_mul_f32 v[54:55], v[54:55], v[110:111]
	v_pk_mul_f32 v[50:51], v[50:51], v[114:115]
	v_pk_mul_f32 v[48:49], v[48:49], v[112:113]
	v_pk_mul_f32 v[44:45], v[44:45], v[100:101]
	v_pk_mul_f32 v[40:41], v[40:41], v[104:105]
	v_pk_mul_f32 v[36:37], v[36:37], v[108:109]
	v_pk_mul_f32 v[46:47], v[46:47], v[102:103]
	v_pk_mul_f32 v[42:43], v[42:43], v[106:107]
	v_pk_mul_f32 v[38:39], v[38:39], v[110:111]
	v_pk_mul_f32 v[34:35], v[34:35], v[114:115]
	v_pk_mul_f32 v[32:33], v[32:33], v[112:113]
	v_pk_mul_f32 v[28:29], v[28:29], v[100:101]
	v_pk_mul_f32 v[24:25], v[24:25], v[104:105]
	v_pk_mul_f32 v[20:21], v[20:21], v[108:109]
	v_pk_mul_f32 v[30:31], v[30:31], v[102:103]
	v_pk_mul_f32 v[26:27], v[26:27], v[106:107]
	v_pk_mul_f32 v[22:23], v[22:23], v[110:111]
	v_pk_mul_f32 v[18:19], v[18:19], v[114:115]
	v_pk_mul_f32 v[16:17], v[16:17], v[112:113]
